# layer-1 weight conversion segment after LRU-out re-dealt over workgroups 128..255 (first idle block 32 -> 128)
# speedup vs baseline: 1.1453x; 1.0020x over previous
.LBB0_479:
	v_readlane_b32 s0, v244, 15
	v_readlane_b32 s1, v244, 16
	s_andn2_b64 vcc, exec, s[0:1]
	s_cbranch_vccnz .LBB0_497
	v_mov_b32_e32 v2, v180
	v_readlane_b32 s0, v246, 0
	s_cmp_lt_i32 s0, 0x80
	s_cbranch_scc1 .LBB0_497
	v_ashrrev_i32_e32 v4, 6, v2
	v_lshl_add_u32 v0, s0, 3, v4
	v_add_u32_e32 v0, 0xfffffc00, v0
	s_movk_i32 s1, 0x800
	v_cmp_gt_u32_e32 vcc, s1, v0
	s_and_saveexec_b64 s[20:21], vcc
	s_cbranch_execz .LBB0_496
	s_add_u32 s22, s84, 0x100000
	s_addc_u32 s23, s12, 0
	s_add_u32 s24, s84, 0x3b00000
	v_add_u32_e32 v3, 0x7040, v0
	s_waitcnt lgkmcnt(0)
	v_bfe_u32 v1, v2, 5, 1
	v_and_b32_e32 v0, 31, v2
	v_bfe_u32 v9, v2, 3, 3
	v_lshlrev_b32_e32 v2, 3, v2
	s_addc_u32 s25, s12, 0
	v_lshl_add_u32 v5, v4, 14, 0
	v_lshlrev_b32_e32 v6, 2, v0
	v_mul_u32_u24_e32 v7, 0x84, v1
	v_and_b32_e32 v2, 56, v2
	s_add_u32 s26, s84, 0x4b00000
	v_add3_u32 v8, v5, v6, v7
	v_mul_u32_u24_e32 v6, 0x84, v2
	v_lshlrev_b32_e32 v7, 2, v9
	v_lshlrev_b32_e32 v4, 5, v4
	s_addc_u32 s27, s12, 0
	v_add3_u32 v10, v5, v6, v7
	v_or_b32_e32 v11, 8, v9
	v_or_b32_e32 v12, 24, v9
	v_or_b32_e32 v13, 16, v9
	v_lshl_add_u32 v14, s0, 8, v4
	s_mov_b64 s[28:29], 0
	s_branch .LBB0_484
.LBB0_483:
	s_or_b64 exec, exec, s[4:5]
	s_movk_i32 s0, 0x743f
	v_add_u32_e32 v4, 0x400, v3
	v_cmp_lt_i32_e32 vcc, s0, v3
	v_add_u32_e32 v14, 0x8000, v14
	s_or_b64 s[28:29], vcc, s[28:29]
	v_mov_b32_e32 v3, v4
	s_andn2_b64 exec, exec, s[28:29]
	s_cbranch_execz .LBB0_496
.LBB0_484:
	s_movk_i32 s0, 0x383f
	v_cmp_lt_i32_e32 vcc, s0, v3
	s_and_saveexec_b64 s[0:1], vcc
	s_xor_b64 s[30:31], exec, s[0:1]
	s_cbranch_execz .LBB0_494
	s_movk_i32 s0, 0x483f
	v_cmp_lt_u32_e32 vcc, s0, v3
	s_and_saveexec_b64 s[0:1], vcc
	s_xor_b64 s[34:35], exec, s[0:1]
	s_cbranch_execz .LBB0_491
	s_movk_i32 s0, 0x683f
	v_cmp_lt_u32_e32 vcc, s0, v3
	s_and_saveexec_b64 s[0:1], vcc
	s_xor_b64 s[4:5], exec, s[0:1]
	s_cbranch_execz .LBB0_488
	v_add_u32_e32 v15, 0xffff97c0, v3
	v_and_b32_e32 v144, 0xfffff800, v15
	v_and_b32_e32 v18, 0x7c0, v15
	v_add_u32_e32 v15, 0xd8800, v14
	v_lshlrev_b64 v[4:5], 13, v[144:145]
	v_and_b32_e32 v15, 0x7e0, v15
	v_lshl_add_u64 v[6:7], s[40:41], 0, v[4:5]
	v_lshlrev_b64 v[4:5], 12, v[144:145]
	v_lshlrev_b32_e32 v144, 2, v15
	v_or_b32_e32 v16, v18, v1
	v_lshl_add_u64 v[6:7], v[6:7], 0, v[144:145]
	v_lshlrev_b32_e32 v144, 2, v0
	v_lshl_add_u64 v[6:7], v[6:7], 0, v[144:145]
	v_lshlrev_b32_e32 v144, 13, v16
	v_lshl_add_u64 v[6:7], v[6:7], 0, v[144:145]
	s_movk_i32 s0, 0x4000
	v_add_co_u32_e32 v16, vcc, s0, v6
	s_mov_b32 s0, 0x8000
	s_nop 0
	v_addc_co_u32_e32 v17, vcc, 0, v7, vcc
	flat_load_dword v19, v[6:7]
	flat_load_dword v20, v[16:17]
	v_add_co_u32_e32 v16, vcc, s0, v6
	s_mov_b32 s0, 0xc000
	s_nop 0
	v_addc_co_u32_e32 v17, vcc, 0, v7, vcc
	flat_load_dword v21, v[16:17]
	v_add_co_u32_e32 v16, vcc, s0, v6
	s_mov_b32 s0, 0x10000
	s_nop 0
	v_addc_co_u32_e32 v17, vcc, 0, v7, vcc
	flat_load_dword v22, v[16:17]
	v_add_co_u32_e32 v16, vcc, s0, v6
	s_mov_b32 s0, 0x14000
	s_nop 0
	v_addc_co_u32_e32 v17, vcc, 0, v7, vcc
	flat_load_dword v23, v[16:17]
	v_add_co_u32_e32 v16, vcc, s0, v6
	s_mov_b32 s0, 0x1c000
	s_nop 0
	v_addc_co_u32_e32 v17, vcc, 0, v7, vcc
	flat_load_dword v24, v[16:17]
	v_add_co_u32_e32 v16, vcc, s89, v6
	v_lshlrev_b32_e32 v144, 1, v18
	s_nop 0
	v_addc_co_u32_e32 v17, vcc, 0, v7, vcc
	flat_load_dword v25, v[16:17]
	v_add_co_u32_e32 v16, vcc, s0, v6
	s_mov_b32 s0, 0x20000
	s_nop 0
	v_addc_co_u32_e32 v17, vcc, 0, v7, vcc
	flat_load_dword v26, v[16:17]
	v_add_co_u32_e32 v16, vcc, s0, v6
	s_mov_b32 s0, 0x24000
	s_nop 0
	v_addc_co_u32_e32 v17, vcc, 0, v7, vcc
	flat_load_dword v27, v[16:17]
	v_add_co_u32_e32 v16, vcc, s0, v6
	s_mov_b32 s0, 0x28000
	s_nop 0
	v_addc_co_u32_e32 v17, vcc, 0, v7, vcc
	flat_load_dword v28, v[16:17]
	v_add_co_u32_e32 v16, vcc, s0, v6
	s_mov_b32 s0, 0x2c000
	s_nop 0
	v_addc_co_u32_e32 v17, vcc, 0, v7, vcc
	flat_load_dword v29, v[16:17]
	v_add_co_u32_e32 v16, vcc, s0, v6
	s_mov_b32 s0, 0x30000
	s_nop 0
	v_addc_co_u32_e32 v17, vcc, 0, v7, vcc
	flat_load_dword v30, v[16:17]
	v_add_co_u32_e32 v16, vcc, s0, v6
	s_mov_b32 s0, 0x34000
	s_nop 0
	v_addc_co_u32_e32 v17, vcc, 0, v7, vcc
	flat_load_dword v31, v[16:17]
	v_add_co_u32_e32 v16, vcc, s0, v6
	s_mov_b32 s0, 0x38000
	s_nop 0
	v_addc_co_u32_e32 v17, vcc, 0, v7, vcc
	flat_load_dword v32, v[16:17]
	v_add_co_u32_e32 v16, vcc, s0, v6
	s_mov_b32 s0, 0x3c000
	s_nop 0
	v_addc_co_u32_e32 v17, vcc, 0, v7, vcc
	flat_load_dword v33, v[16:17]
	v_add_co_u32_e32 v16, vcc, s0, v6
	s_mov_b32 s0, 0x40000
	s_nop 0
	v_addc_co_u32_e32 v17, vcc, 0, v7, vcc
	flat_load_dword v34, v[16:17]
	v_add_co_u32_e32 v16, vcc, s0, v6
	s_mov_b32 s0, 0x44000
	s_nop 0
	v_addc_co_u32_e32 v17, vcc, 0, v7, vcc
	flat_load_dword v35, v[16:17]
	v_add_co_u32_e32 v16, vcc, s0, v6
	s_mov_b32 s0, 0x48000
	s_nop 0
	v_addc_co_u32_e32 v17, vcc, 0, v7, vcc
	flat_load_dword v36, v[16:17]
	v_add_co_u32_e32 v16, vcc, s0, v6
	s_mov_b32 s0, 0x4c000
	s_nop 0
	v_addc_co_u32_e32 v17, vcc, 0, v7, vcc
	flat_load_dword v37, v[16:17]
	v_add_co_u32_e32 v16, vcc, s0, v6
	s_mov_b32 s0, 0x50000
	s_nop 0
	v_addc_co_u32_e32 v17, vcc, 0, v7, vcc
	flat_load_dword v38, v[16:17]
	v_add_co_u32_e32 v16, vcc, s0, v6
	s_mov_b32 s0, 0x54000
	s_nop 0
	v_addc_co_u32_e32 v17, vcc, 0, v7, vcc
	flat_load_dword v39, v[16:17]
	v_add_co_u32_e32 v16, vcc, s0, v6
	s_mov_b32 s0, 0x58000
	s_nop 0
	v_addc_co_u32_e32 v17, vcc, 0, v7, vcc
	flat_load_dword v40, v[16:17]
	v_add_co_u32_e32 v16, vcc, s0, v6
	s_mov_b32 s0, 0x5c000
	s_nop 0
	v_addc_co_u32_e32 v17, vcc, 0, v7, vcc
	flat_load_dword v41, v[16:17]
	v_add_co_u32_e32 v16, vcc, s0, v6
	s_mov_b32 s0, 0x60000
	s_nop 0
	v_addc_co_u32_e32 v17, vcc, 0, v7, vcc
	flat_load_dword v42, v[16:17]
	v_add_co_u32_e32 v16, vcc, s0, v6
	s_mov_b32 s0, 0x64000
	s_nop 0
	v_addc_co_u32_e32 v17, vcc, 0, v7, vcc
	flat_load_dword v43, v[16:17]
	v_add_co_u32_e32 v16, vcc, s0, v6
	s_mov_b32 s0, 0x68000
	s_nop 0
	v_addc_co_u32_e32 v17, vcc, 0, v7, vcc
	flat_load_dword v44, v[16:17]
	v_add_co_u32_e32 v16, vcc, s0, v6
	s_mov_b32 s0, 0x6c000
	s_nop 0
	v_addc_co_u32_e32 v17, vcc, 0, v7, vcc
	flat_load_dword v45, v[16:17]
	v_add_co_u32_e32 v16, vcc, s0, v6
	s_mov_b32 s0, 0x70000
	s_nop 0
	v_addc_co_u32_e32 v17, vcc, 0, v7, vcc
	flat_load_dword v46, v[16:17]
	v_add_co_u32_e32 v16, vcc, s0, v6
	s_mov_b32 s0, 0x74000
	s_nop 0
	v_addc_co_u32_e32 v17, vcc, 0, v7, vcc
	flat_load_dword v47, v[16:17]
	v_add_co_u32_e32 v16, vcc, s0, v6
	s_mov_b32 s0, 0x78000
	s_nop 0
	v_addc_co_u32_e32 v17, vcc, 0, v7, vcc
	flat_load_dword v48, v[16:17]
	v_add_co_u32_e32 v16, vcc, s0, v6
	s_mov_b32 s0, 0x7c000
	s_nop 0
	v_addc_co_u32_e32 v17, vcc, 0, v7, vcc
	v_add_co_u32_e32 v6, vcc, s0, v6
	flat_load_dword v16, v[16:17]
	s_nop 0
	v_addc_co_u32_e32 v7, vcc, 0, v7, vcc
	flat_load_dword v6, v[6:7]
	v_add_u32_e32 v7, 0x400, v8
	s_waitcnt vmcnt(0) lgkmcnt(0)
	ds_write2_b32 v8, v19, v20 offset1:66
	ds_write2_b32 v8, v21, v22 offset0:132 offset1:198
	ds_write2_b32 v7, v23, v24 offset0:8 offset1:74
	ds_write2_b32 v7, v25, v26 offset0:140 offset1:206
	v_add_u32_e32 v7, 0x800, v8
	ds_write2_b32 v7, v27, v28 offset0:16 offset1:82
	ds_write2_b32 v7, v29, v30 offset0:148 offset1:214
	v_add_u32_e32 v7, 0xc00, v8
	ds_write2_b32 v7, v31, v32 offset0:24 offset1:90
	ds_write2_b32 v7, v33, v34 offset0:156 offset1:222
	v_add_u32_e32 v7, 0x1000, v8
	ds_write2_b32 v7, v35, v36 offset0:32 offset1:98
	ds_write2_b32 v7, v37, v38 offset0:164 offset1:230
	v_add_u32_e32 v7, 0x1400, v8
	ds_write2_b32 v7, v39, v40 offset0:40 offset1:106
	ds_write2_b32 v7, v41, v42 offset0:172 offset1:238
	v_add_u32_e32 v7, 0x1800, v8
	ds_write2_b32 v7, v43, v44 offset0:48 offset1:114
	ds_write2_b32 v7, v45, v46 offset0:180 offset1:246
	v_add_u32_e32 v7, 0x1c00, v8
	ds_write2_b32 v7, v47, v48 offset0:56 offset1:122
	ds_write2_b32 v7, v16, v6 offset0:188 offset1:254
	s_waitcnt lgkmcnt(0)
	ds_read_b32 v6, v10
	ds_read_b32 v7, v10 offset:132
	v_lshl_add_u64 v[4:5], s[8:9], 0, v[4:5]
	v_lshl_add_u64 v[4:5], v[4:5], 0, v[144:145]
	v_lshlrev_b32_e32 v144, 1, v2
	s_waitcnt lgkmcnt(1)
	v_add_u32_e32 v6, 0x8000, v6
	s_waitcnt lgkmcnt(0)
	v_add_u32_e32 v7, 0x8000, v7
	v_perm_b32 v16, v7, v6, s81
	ds_read_b32 v6, v10 offset:264
	ds_read_b32 v7, v10 offset:396
	v_lshl_add_u64 v[4:5], v[4:5], 0, v[144:145]
	s_waitcnt lgkmcnt(1)
	v_add_u32_e32 v6, 0x8000, v6
	s_waitcnt lgkmcnt(0)
	v_add_u32_e32 v7, 0x8000, v7
	v_perm_b32 v17, v7, v6, s81
	ds_read_b32 v6, v10 offset:528
	ds_read_b32 v7, v10 offset:660
	s_waitcnt lgkmcnt(1)
	v_add_u32_e32 v6, 0x8000, v6
	s_waitcnt lgkmcnt(0)
	v_add_u32_e32 v7, 0x8000, v7
	v_perm_b32 v18, v7, v6, s81
	ds_read_b32 v6, v10 offset:792
	ds_read_b32 v7, v10 offset:924
	s_waitcnt lgkmcnt(1)
	v_add_u32_e32 v6, 0x8000, v6
	s_waitcnt lgkmcnt(0)
	v_add_u32_e32 v7, 0x8000, v7
	v_perm_b32 v19, v7, v6, s81
	v_or_b32_e32 v6, v15, v9
	v_lshlrev_b32_e32 v144, 12, v6
	v_lshl_add_u64 v[6:7], v[4:5], 0, v[144:145]
	flat_store_dwordx4 v[6:7], v[16:19]
	ds_read_b32 v6, v10 offset:32
	ds_read_b32 v7, v10 offset:164
	s_waitcnt lgkmcnt(0)
	v_add_u32_e32 v6, 0x8000, v6
	v_add_u32_e32 v7, 0x8000, v7
	v_perm_b32 v16, v7, v6, s81
	ds_read_b32 v6, v10 offset:296
	ds_read_b32 v7, v10 offset:428
	s_waitcnt lgkmcnt(0)
	v_add_u32_e32 v6, 0x8000, v6
	v_add_u32_e32 v7, 0x8000, v7
	v_perm_b32 v17, v7, v6, s81
	ds_read_b32 v6, v10 offset:560
	ds_read_b32 v7, v10 offset:692
	s_waitcnt lgkmcnt(0)
	v_add_u32_e32 v6, 0x8000, v6
	v_add_u32_e32 v7, 0x8000, v7
	v_perm_b32 v18, v7, v6, s81
	ds_read_b32 v6, v10 offset:824
	ds_read_b32 v7, v10 offset:956
	s_waitcnt lgkmcnt(0)
	v_add_u32_e32 v6, 0x8000, v6
	v_add_u32_e32 v7, 0x8000, v7
	v_perm_b32 v19, v7, v6, s81
	v_or_b32_e32 v6, v15, v11
	v_lshlrev_b32_e32 v144, 12, v6
	v_lshl_add_u64 v[6:7], v[4:5], 0, v[144:145]
	flat_store_dwordx4 v[6:7], v[16:19]
	ds_read_b32 v6, v10 offset:64
	ds_read_b32 v7, v10 offset:196
	s_waitcnt lgkmcnt(0)
	v_add_u32_e32 v6, 0x8000, v6
	v_add_u32_e32 v7, 0x8000, v7
	v_perm_b32 v16, v7, v6, s81
	ds_read_b32 v6, v10 offset:328
	ds_read_b32 v7, v10 offset:460
	s_waitcnt lgkmcnt(0)
	v_add_u32_e32 v6, 0x8000, v6
	v_add_u32_e32 v7, 0x8000, v7
	v_perm_b32 v17, v7, v6, s81
	ds_read_b32 v6, v10 offset:592
	ds_read_b32 v7, v10 offset:724
	s_waitcnt lgkmcnt(0)
	v_add_u32_e32 v6, 0x8000, v6
	v_add_u32_e32 v7, 0x8000, v7
	v_perm_b32 v18, v7, v6, s81
	ds_read_b32 v6, v10 offset:856
	ds_read_b32 v7, v10 offset:988
	s_waitcnt lgkmcnt(0)
	v_add_u32_e32 v6, 0x8000, v6
	v_add_u32_e32 v7, 0x8000, v7
	v_perm_b32 v19, v7, v6, s81
	v_or_b32_e32 v6, v15, v13
	v_lshlrev_b32_e32 v144, 12, v6
	v_lshl_add_u64 v[6:7], v[4:5], 0, v[144:145]
	flat_store_dwordx4 v[6:7], v[16:19]
	ds_read_b32 v6, v10 offset:96
	ds_read_b32 v7, v10 offset:228
	s_waitcnt lgkmcnt(0)
	v_add_u32_e32 v6, 0x8000, v6
	v_add_u32_e32 v7, 0x8000, v7
	v_perm_b32 v16, v7, v6, s81
	ds_read_b32 v6, v10 offset:360
	ds_read_b32 v7, v10 offset:492
	s_waitcnt lgkmcnt(0)
	v_add_u32_e32 v6, 0x8000, v6
	v_add_u32_e32 v7, 0x8000, v7
	v_perm_b32 v17, v7, v6, s81
	ds_read_b32 v6, v10 offset:624
	ds_read_b32 v7, v10 offset:756
	s_waitcnt lgkmcnt(0)
	v_add_u32_e32 v6, 0x8000, v6
	v_add_u32_e32 v7, 0x8000, v7
	v_perm_b32 v18, v7, v6, s81
	ds_read_b32 v6, v10 offset:888
	ds_read_b32 v7, v10 offset:1020
	s_waitcnt lgkmcnt(0)
	v_add_u32_e32 v6, 0x8000, v6
	v_add_u32_e32 v7, 0x8000, v7
	v_perm_b32 v19, v7, v6, s81
	v_or_b32_e32 v6, v15, v12
	v_lshlrev_b32_e32 v144, 12, v6
	v_lshl_add_u64 v[4:5], v[4:5], 0, v[144:145]
	flat_store_dwordx4 v[4:5], v[16:19]
	s_waitcnt lgkmcnt(0)
.LBB0_488:
	s_andn2_saveexec_b64 s[4:5], s[4:5]
	s_cbranch_execz .LBB0_490
	v_add_u32_e32 v15, 0xffffb7c0, v3
	v_lshrrev_b32_e32 v144, 12, v15
	v_lshrrev_b32_e32 v15, 1, v15
	v_and_b32_e32 v18, 0x7c0, v15
	v_add_u32_e32 v15, 0x48000, v14
	v_lshlrev_b64 v[4:5], 25, v[144:145]
	v_and_b32_e32 v15, 0xfe0, v15
	v_lshl_add_u64 v[6:7], s[38:39], 0, v[4:5]
	v_lshlrev_b64 v[4:5], 24, v[144:145]
	v_lshlrev_b32_e32 v144, 2, v15
	v_or_b32_e32 v16, v18, v1
	v_lshl_add_u64 v[6:7], v[6:7], 0, v[144:145]
	v_lshlrev_b32_e32 v144, 2, v0
	v_lshl_add_u64 v[6:7], v[6:7], 0, v[144:145]
	v_lshlrev_b32_e32 v144, 14, v16
	v_lshl_add_u64 v[6:7], v[6:7], 0, v[144:145]
	s_mov_b32 s0, 0x8000
	v_add_co_u32_e32 v16, vcc, s0, v6
	s_mov_b32 s0, 0x10000
	s_nop 0
	v_addc_co_u32_e32 v17, vcc, 0, v7, vcc
	flat_load_dword v19, v[6:7]
	flat_load_dword v20, v[16:17]
	v_add_co_u32_e32 v16, vcc, s0, v6
	s_mov_b32 s0, 0x20000
	s_nop 0
	v_addc_co_u32_e32 v17, vcc, 0, v7, vcc
	flat_load_dword v21, v[16:17]
	v_add_co_u32_e32 v16, vcc, s89, v6
	v_lshlrev_b32_e32 v144, 1, v18
	s_nop 0
	v_addc_co_u32_e32 v17, vcc, 0, v7, vcc
	flat_load_dword v22, v[16:17]
	v_add_co_u32_e32 v16, vcc, s0, v6
	s_mov_b32 s0, 0x28000
	s_nop 0
	v_addc_co_u32_e32 v17, vcc, 0, v7, vcc
	flat_load_dword v23, v[16:17]
	v_add_co_u32_e32 v16, vcc, s0, v6
	s_mov_b32 s0, 0x30000
	s_nop 0
	v_addc_co_u32_e32 v17, vcc, 0, v7, vcc
	flat_load_dword v24, v[16:17]
	v_add_co_u32_e32 v16, vcc, s0, v6
	s_mov_b32 s0, 0x38000
	s_nop 0
	v_addc_co_u32_e32 v17, vcc, 0, v7, vcc
	flat_load_dword v25, v[16:17]
	v_add_co_u32_e32 v16, vcc, s0, v6
	s_mov_b32 s0, 0x40000
	s_nop 0
	v_addc_co_u32_e32 v17, vcc, 0, v7, vcc
	flat_load_dword v26, v[16:17]
	v_add_co_u32_e32 v16, vcc, s0, v6
	s_mov_b32 s0, 0x48000
	s_nop 0
	v_addc_co_u32_e32 v17, vcc, 0, v7, vcc
	flat_load_dword v27, v[16:17]
	v_add_co_u32_e32 v16, vcc, s0, v6
	s_mov_b32 s0, 0x50000
	s_nop 0
	v_addc_co_u32_e32 v17, vcc, 0, v7, vcc
	flat_load_dword v28, v[16:17]
	v_add_co_u32_e32 v16, vcc, s0, v6
	s_mov_b32 s0, 0x58000
	s_nop 0
	v_addc_co_u32_e32 v17, vcc, 0, v7, vcc
	flat_load_dword v29, v[16:17]
	v_add_co_u32_e32 v16, vcc, s0, v6
	s_mov_b32 s0, 0x60000
	s_nop 0
	v_addc_co_u32_e32 v17, vcc, 0, v7, vcc
	flat_load_dword v30, v[16:17]
	v_add_co_u32_e32 v16, vcc, s0, v6
	s_mov_b32 s0, 0x68000
	s_nop 0
	v_addc_co_u32_e32 v17, vcc, 0, v7, vcc
	flat_load_dword v31, v[16:17]
	v_add_co_u32_e32 v16, vcc, s0, v6
	s_mov_b32 s0, 0x70000
	s_nop 0
	v_addc_co_u32_e32 v17, vcc, 0, v7, vcc
	flat_load_dword v32, v[16:17]
	v_add_co_u32_e32 v16, vcc, s0, v6
	s_mov_b32 s0, 0x78000
	s_nop 0
	v_addc_co_u32_e32 v17, vcc, 0, v7, vcc
	flat_load_dword v33, v[16:17]
	v_add_co_u32_e32 v16, vcc, s0, v6
	s_mov_b32 s0, 0x80000
	s_nop 0
	v_addc_co_u32_e32 v17, vcc, 0, v7, vcc
	flat_load_dword v34, v[16:17]
	v_add_co_u32_e32 v16, vcc, s0, v6
	s_mov_b32 s0, 0x88000
	s_nop 0
	v_addc_co_u32_e32 v17, vcc, 0, v7, vcc
	flat_load_dword v35, v[16:17]
	v_add_co_u32_e32 v16, vcc, s0, v6
	s_mov_b32 s0, 0x90000
	s_nop 0
	v_addc_co_u32_e32 v17, vcc, 0, v7, vcc
	flat_load_dword v36, v[16:17]
	v_add_co_u32_e32 v16, vcc, s0, v6
	s_mov_b32 s0, 0x98000
	s_nop 0
	v_addc_co_u32_e32 v17, vcc, 0, v7, vcc
	flat_load_dword v37, v[16:17]
	v_add_co_u32_e32 v16, vcc, s0, v6
	s_mov_b32 s0, 0xa0000
	s_nop 0
	v_addc_co_u32_e32 v17, vcc, 0, v7, vcc
	flat_load_dword v38, v[16:17]
	v_add_co_u32_e32 v16, vcc, s0, v6
	s_mov_b32 s0, 0xa8000
	s_nop 0
	v_addc_co_u32_e32 v17, vcc, 0, v7, vcc
	flat_load_dword v39, v[16:17]
	v_add_co_u32_e32 v16, vcc, s0, v6
	s_mov_b32 s0, 0xb0000
	s_nop 0
	v_addc_co_u32_e32 v17, vcc, 0, v7, vcc
	flat_load_dword v40, v[16:17]
	v_add_co_u32_e32 v16, vcc, s0, v6
	s_mov_b32 s0, 0xb8000
	s_nop 0
	v_addc_co_u32_e32 v17, vcc, 0, v7, vcc
	flat_load_dword v41, v[16:17]
	v_add_co_u32_e32 v16, vcc, s0, v6
	s_mov_b32 s0, 0xc0000
	s_nop 0
	v_addc_co_u32_e32 v17, vcc, 0, v7, vcc
	flat_load_dword v42, v[16:17]
	v_add_co_u32_e32 v16, vcc, s0, v6
	s_mov_b32 s0, 0xc8000
	s_nop 0
	v_addc_co_u32_e32 v17, vcc, 0, v7, vcc
	flat_load_dword v43, v[16:17]
	v_add_co_u32_e32 v16, vcc, s0, v6
	s_mov_b32 s0, 0xd0000
	s_nop 0
	v_addc_co_u32_e32 v17, vcc, 0, v7, vcc
	flat_load_dword v44, v[16:17]
	v_add_co_u32_e32 v16, vcc, s0, v6
	s_mov_b32 s0, 0xd8000
	s_nop 0
	v_addc_co_u32_e32 v17, vcc, 0, v7, vcc
	flat_load_dword v45, v[16:17]
	v_add_co_u32_e32 v16, vcc, s0, v6
	s_mov_b32 s0, 0xe0000
	s_nop 0
	v_addc_co_u32_e32 v17, vcc, 0, v7, vcc
	flat_load_dword v46, v[16:17]
	v_add_co_u32_e32 v16, vcc, s0, v6
	s_mov_b32 s0, 0xe8000
	s_nop 0
	v_addc_co_u32_e32 v17, vcc, 0, v7, vcc
	flat_load_dword v47, v[16:17]
	v_add_co_u32_e32 v16, vcc, s0, v6
	s_mov_b32 s0, 0xf0000
	s_nop 0
	v_addc_co_u32_e32 v17, vcc, 0, v7, vcc
	flat_load_dword v48, v[16:17]
	v_add_co_u32_e32 v16, vcc, s0, v6
	s_mov_b32 s0, 0xf8000
	s_nop 0
	v_addc_co_u32_e32 v17, vcc, 0, v7, vcc
	v_add_co_u32_e32 v6, vcc, s0, v6
	flat_load_dword v16, v[16:17]
	s_nop 0
	v_addc_co_u32_e32 v7, vcc, 0, v7, vcc
	flat_load_dword v6, v[6:7]
	v_add_u32_e32 v7, 0x400, v8
	s_waitcnt vmcnt(0) lgkmcnt(0)
	ds_write2_b32 v8, v19, v20 offset1:66
	ds_write2_b32 v8, v21, v22 offset0:132 offset1:198
	ds_write2_b32 v7, v23, v24 offset0:8 offset1:74
	ds_write2_b32 v7, v25, v26 offset0:140 offset1:206
	v_add_u32_e32 v7, 0x800, v8
	ds_write2_b32 v7, v27, v28 offset0:16 offset1:82
	ds_write2_b32 v7, v29, v30 offset0:148 offset1:214
	v_add_u32_e32 v7, 0xc00, v8
	ds_write2_b32 v7, v31, v32 offset0:24 offset1:90
	ds_write2_b32 v7, v33, v34 offset0:156 offset1:222
	v_add_u32_e32 v7, 0x1000, v8
	ds_write2_b32 v7, v35, v36 offset0:32 offset1:98
	ds_write2_b32 v7, v37, v38 offset0:164 offset1:230
	v_add_u32_e32 v7, 0x1400, v8
	ds_write2_b32 v7, v39, v40 offset0:40 offset1:106
	ds_write2_b32 v7, v41, v42 offset0:172 offset1:238
	v_add_u32_e32 v7, 0x1800, v8
	ds_write2_b32 v7, v43, v44 offset0:48 offset1:114
	ds_write2_b32 v7, v45, v46 offset0:180 offset1:246
	v_add_u32_e32 v7, 0x1c00, v8
	ds_write2_b32 v7, v47, v48 offset0:56 offset1:122
	ds_write2_b32 v7, v16, v6 offset0:188 offset1:254
	s_waitcnt lgkmcnt(0)
	ds_read_b32 v6, v10
	ds_read_b32 v7, v10 offset:132
	v_lshl_add_u64 v[4:5], s[26:27], 0, v[4:5]
	v_lshl_add_u64 v[4:5], v[4:5], 0, v[144:145]
	v_lshlrev_b32_e32 v144, 1, v2
	s_waitcnt lgkmcnt(1)
	v_add_u32_e32 v6, 0x8000, v6
	s_waitcnt lgkmcnt(0)
	v_add_u32_e32 v7, 0x8000, v7
	v_perm_b32 v16, v7, v6, s81
	ds_read_b32 v6, v10 offset:264
	ds_read_b32 v7, v10 offset:396
	v_lshl_add_u64 v[4:5], v[4:5], 0, v[144:145]
	s_waitcnt lgkmcnt(1)
	v_add_u32_e32 v6, 0x8000, v6
	s_waitcnt lgkmcnt(0)
	v_add_u32_e32 v7, 0x8000, v7
	v_perm_b32 v17, v7, v6, s81
	ds_read_b32 v6, v10 offset:528
	ds_read_b32 v7, v10 offset:660
	s_waitcnt lgkmcnt(1)
	v_add_u32_e32 v6, 0x8000, v6
	s_waitcnt lgkmcnt(0)
	v_add_u32_e32 v7, 0x8000, v7
	v_perm_b32 v18, v7, v6, s81
	ds_read_b32 v6, v10 offset:792
	ds_read_b32 v7, v10 offset:924
	s_waitcnt lgkmcnt(1)
	v_add_u32_e32 v6, 0x8000, v6
	s_waitcnt lgkmcnt(0)
	v_add_u32_e32 v7, 0x8000, v7
	v_perm_b32 v19, v7, v6, s81
	v_or_b32_e32 v6, v15, v9
	v_lshlrev_b32_e32 v144, 12, v6
	v_lshl_add_u64 v[6:7], v[4:5], 0, v[144:145]
	flat_store_dwordx4 v[6:7], v[16:19]
	ds_read_b32 v6, v10 offset:32
	ds_read_b32 v7, v10 offset:164
	s_waitcnt lgkmcnt(0)
	v_add_u32_e32 v6, 0x8000, v6
	v_add_u32_e32 v7, 0x8000, v7
	v_perm_b32 v16, v7, v6, s81
	ds_read_b32 v6, v10 offset:296
	ds_read_b32 v7, v10 offset:428
	s_waitcnt lgkmcnt(0)
	v_add_u32_e32 v6, 0x8000, v6
	v_add_u32_e32 v7, 0x8000, v7
	v_perm_b32 v17, v7, v6, s81
	ds_read_b32 v6, v10 offset:560
	ds_read_b32 v7, v10 offset:692
	s_waitcnt lgkmcnt(0)
	v_add_u32_e32 v6, 0x8000, v6
	v_add_u32_e32 v7, 0x8000, v7
	v_perm_b32 v18, v7, v6, s81
	ds_read_b32 v6, v10 offset:824
	ds_read_b32 v7, v10 offset:956
	s_waitcnt lgkmcnt(0)
	v_add_u32_e32 v6, 0x8000, v6
	v_add_u32_e32 v7, 0x8000, v7
	v_perm_b32 v19, v7, v6, s81
	v_or_b32_e32 v6, v15, v11
	v_lshlrev_b32_e32 v144, 12, v6
	v_lshl_add_u64 v[6:7], v[4:5], 0, v[144:145]
	flat_store_dwordx4 v[6:7], v[16:19]
	ds_read_b32 v6, v10 offset:64
	ds_read_b32 v7, v10 offset:196
	s_waitcnt lgkmcnt(0)
	v_add_u32_e32 v6, 0x8000, v6
	v_add_u32_e32 v7, 0x8000, v7
	v_perm_b32 v16, v7, v6, s81
	ds_read_b32 v6, v10 offset:328
	ds_read_b32 v7, v10 offset:460
	s_waitcnt lgkmcnt(0)
	v_add_u32_e32 v6, 0x8000, v6
	v_add_u32_e32 v7, 0x8000, v7
	v_perm_b32 v17, v7, v6, s81
	ds_read_b32 v6, v10 offset:592
	ds_read_b32 v7, v10 offset:724
	s_waitcnt lgkmcnt(0)
	v_add_u32_e32 v6, 0x8000, v6
	v_add_u32_e32 v7, 0x8000, v7
	v_perm_b32 v18, v7, v6, s81
	ds_read_b32 v6, v10 offset:856
	ds_read_b32 v7, v10 offset:988
	s_waitcnt lgkmcnt(0)
	v_add_u32_e32 v6, 0x8000, v6
	v_add_u32_e32 v7, 0x8000, v7
	v_perm_b32 v19, v7, v6, s81
	v_or_b32_e32 v6, v15, v13
	v_lshlrev_b32_e32 v144, 12, v6
	v_lshl_add_u64 v[6:7], v[4:5], 0, v[144:145]
	flat_store_dwordx4 v[6:7], v[16:19]
	ds_read_b32 v6, v10 offset:96
	ds_read_b32 v7, v10 offset:228
	s_waitcnt lgkmcnt(0)
	v_add_u32_e32 v6, 0x8000, v6
	v_add_u32_e32 v7, 0x8000, v7
	v_perm_b32 v16, v7, v6, s81
	ds_read_b32 v6, v10 offset:360
	ds_read_b32 v7, v10 offset:492
	s_waitcnt lgkmcnt(0)
	v_add_u32_e32 v6, 0x8000, v6
	v_add_u32_e32 v7, 0x8000, v7
	v_perm_b32 v17, v7, v6, s81
	ds_read_b32 v6, v10 offset:624
	ds_read_b32 v7, v10 offset:756
	s_waitcnt lgkmcnt(0)
	v_add_u32_e32 v6, 0x8000, v6
	v_add_u32_e32 v7, 0x8000, v7
	v_perm_b32 v18, v7, v6, s81
	ds_read_b32 v6, v10 offset:888
	ds_read_b32 v7, v10 offset:1020
	s_waitcnt lgkmcnt(0)
	v_add_u32_e32 v6, 0x8000, v6
	v_add_u32_e32 v7, 0x8000, v7
	v_perm_b32 v19, v7, v6, s81
	v_or_b32_e32 v6, v15, v12
	v_lshlrev_b32_e32 v144, 12, v6
	v_lshl_add_u64 v[4:5], v[4:5], 0, v[144:145]
	flat_store_dwordx4 v[4:5], v[16:19]
	s_waitcnt lgkmcnt(0)

.LBB0_491:
	s_andn2_saveexec_b64 s[4:5], s[34:35]
	s_cbranch_execz .LBB0_493
	v_add_u32_e32 v15, 0xffffc7c0, v3
	v_and_b32_e32 v144, 0xfffff800, v15
	v_and_b32_e32 v18, 0x7c0, v15
	v_add_u32_e32 v15, 0xd8800, v14
	v_lshlrev_b64 v[4:5], 13, v[144:145]
	v_and_b32_e32 v15, 0x7e0, v15
	v_lshl_add_u64 v[6:7], s[36:37], 0, v[4:5]
	v_lshlrev_b64 v[4:5], 12, v[144:145]
	v_lshlrev_b32_e32 v144, 2, v15
	v_or_b32_e32 v16, v18, v1
	v_lshl_add_u64 v[6:7], v[6:7], 0, v[144:145]
	v_lshlrev_b32_e32 v144, 2, v0
	v_lshl_add_u64 v[6:7], v[6:7], 0, v[144:145]
	v_lshlrev_b32_e32 v144, 13, v16
	v_lshl_add_u64 v[6:7], v[6:7], 0, v[144:145]
	s_movk_i32 s0, 0x4000
	v_add_co_u32_e32 v16, vcc, s0, v6
	s_mov_b32 s0, 0x8000
	s_nop 0
	v_addc_co_u32_e32 v17, vcc, 0, v7, vcc
	flat_load_dword v19, v[6:7]
	flat_load_dword v20, v[16:17]
	v_add_co_u32_e32 v16, vcc, s0, v6
	s_mov_b32 s0, 0xc000
	s_nop 0
	v_addc_co_u32_e32 v17, vcc, 0, v7, vcc
	flat_load_dword v21, v[16:17]
	v_add_co_u32_e32 v16, vcc, s0, v6
	s_mov_b32 s0, 0x10000
	s_nop 0
	v_addc_co_u32_e32 v17, vcc, 0, v7, vcc
	flat_load_dword v22, v[16:17]
	v_add_co_u32_e32 v16, vcc, s0, v6
	s_mov_b32 s0, 0x14000
	s_nop 0
	v_addc_co_u32_e32 v17, vcc, 0, v7, vcc
	flat_load_dword v23, v[16:17]
	v_add_co_u32_e32 v16, vcc, s0, v6
	s_mov_b32 s0, 0x1c000
	s_nop 0
	v_addc_co_u32_e32 v17, vcc, 0, v7, vcc
	flat_load_dword v24, v[16:17]
	v_add_co_u32_e32 v16, vcc, s89, v6
	v_lshlrev_b32_e32 v144, 1, v18
	s_nop 0
	v_addc_co_u32_e32 v17, vcc, 0, v7, vcc
	flat_load_dword v25, v[16:17]
	v_add_co_u32_e32 v16, vcc, s0, v6
	s_mov_b32 s0, 0x20000
	s_nop 0
	v_addc_co_u32_e32 v17, vcc, 0, v7, vcc
	flat_load_dword v26, v[16:17]
	v_add_co_u32_e32 v16, vcc, s0, v6
	s_mov_b32 s0, 0x24000
	s_nop 0
	v_addc_co_u32_e32 v17, vcc, 0, v7, vcc
	flat_load_dword v27, v[16:17]
	v_add_co_u32_e32 v16, vcc, s0, v6
	s_mov_b32 s0, 0x28000
	s_nop 0
	v_addc_co_u32_e32 v17, vcc, 0, v7, vcc
	flat_load_dword v28, v[16:17]
	v_add_co_u32_e32 v16, vcc, s0, v6
	s_mov_b32 s0, 0x2c000
	s_nop 0
	v_addc_co_u32_e32 v17, vcc, 0, v7, vcc
	flat_load_dword v29, v[16:17]
	v_add_co_u32_e32 v16, vcc, s0, v6
	s_mov_b32 s0, 0x30000
	s_nop 0
	v_addc_co_u32_e32 v17, vcc, 0, v7, vcc
	flat_load_dword v30, v[16:17]
	v_add_co_u32_e32 v16, vcc, s0, v6
	s_mov_b32 s0, 0x34000
	s_nop 0
	v_addc_co_u32_e32 v17, vcc, 0, v7, vcc
	flat_load_dword v31, v[16:17]
	v_add_co_u32_e32 v16, vcc, s0, v6
	s_mov_b32 s0, 0x38000
	s_nop 0
	v_addc_co_u32_e32 v17, vcc, 0, v7, vcc
	flat_load_dword v32, v[16:17]
	v_add_co_u32_e32 v16, vcc, s0, v6
	s_mov_b32 s0, 0x3c000
	s_nop 0
	v_addc_co_u32_e32 v17, vcc, 0, v7, vcc
	flat_load_dword v33, v[16:17]
	v_add_co_u32_e32 v16, vcc, s0, v6
	s_mov_b32 s0, 0x40000
	s_nop 0
	v_addc_co_u32_e32 v17, vcc, 0, v7, vcc
	flat_load_dword v34, v[16:17]
	v_add_co_u32_e32 v16, vcc, s0, v6
	s_mov_b32 s0, 0x44000
	s_nop 0
	v_addc_co_u32_e32 v17, vcc, 0, v7, vcc
	flat_load_dword v35, v[16:17]
	v_add_co_u32_e32 v16, vcc, s0, v6
	s_mov_b32 s0, 0x48000
	s_nop 0
	v_addc_co_u32_e32 v17, vcc, 0, v7, vcc
	flat_load_dword v36, v[16:17]
	v_add_co_u32_e32 v16, vcc, s0, v6
	s_mov_b32 s0, 0x4c000
	s_nop 0
	v_addc_co_u32_e32 v17, vcc, 0, v7, vcc
	flat_load_dword v37, v[16:17]
	v_add_co_u32_e32 v16, vcc, s0, v6
	s_mov_b32 s0, 0x50000
	s_nop 0
	v_addc_co_u32_e32 v17, vcc, 0, v7, vcc
	flat_load_dword v38, v[16:17]
	v_add_co_u32_e32 v16, vcc, s0, v6
	s_mov_b32 s0, 0x54000
	s_nop 0
	v_addc_co_u32_e32 v17, vcc, 0, v7, vcc
	flat_load_dword v39, v[16:17]
	v_add_co_u32_e32 v16, vcc, s0, v6
	s_mov_b32 s0, 0x58000
	s_nop 0
	v_addc_co_u32_e32 v17, vcc, 0, v7, vcc
	flat_load_dword v40, v[16:17]
	v_add_co_u32_e32 v16, vcc, s0, v6
	s_mov_b32 s0, 0x5c000
	s_nop 0
	v_addc_co_u32_e32 v17, vcc, 0, v7, vcc
	flat_load_dword v41, v[16:17]
	v_add_co_u32_e32 v16, vcc, s0, v6
	s_mov_b32 s0, 0x60000
	s_nop 0
	v_addc_co_u32_e32 v17, vcc, 0, v7, vcc
	flat_load_dword v42, v[16:17]
	v_add_co_u32_e32 v16, vcc, s0, v6
	s_mov_b32 s0, 0x64000
	s_nop 0
	v_addc_co_u32_e32 v17, vcc, 0, v7, vcc
	flat_load_dword v43, v[16:17]
	v_add_co_u32_e32 v16, vcc, s0, v6
	s_mov_b32 s0, 0x68000
	s_nop 0
	v_addc_co_u32_e32 v17, vcc, 0, v7, vcc
	flat_load_dword v44, v[16:17]
	v_add_co_u32_e32 v16, vcc, s0, v6
	s_mov_b32 s0, 0x6c000
	s_nop 0
	v_addc_co_u32_e32 v17, vcc, 0, v7, vcc
	flat_load_dword v45, v[16:17]
	v_add_co_u32_e32 v16, vcc, s0, v6
	s_mov_b32 s0, 0x70000
	s_nop 0
	v_addc_co_u32_e32 v17, vcc, 0, v7, vcc
	flat_load_dword v46, v[16:17]
	v_add_co_u32_e32 v16, vcc, s0, v6
	s_mov_b32 s0, 0x74000
	s_nop 0
	v_addc_co_u32_e32 v17, vcc, 0, v7, vcc
	flat_load_dword v47, v[16:17]
	v_add_co_u32_e32 v16, vcc, s0, v6
	s_mov_b32 s0, 0x78000
	s_nop 0
	v_addc_co_u32_e32 v17, vcc, 0, v7, vcc
	flat_load_dword v48, v[16:17]
	v_add_co_u32_e32 v16, vcc, s0, v6
	s_mov_b32 s0, 0x7c000
	s_nop 0
	v_addc_co_u32_e32 v17, vcc, 0, v7, vcc
	v_add_co_u32_e32 v6, vcc, s0, v6
	flat_load_dword v16, v[16:17]
	s_nop 0
	v_addc_co_u32_e32 v7, vcc, 0, v7, vcc
	flat_load_dword v6, v[6:7]
	v_add_u32_e32 v7, 0x400, v8
	s_waitcnt vmcnt(0) lgkmcnt(0)
	ds_write2_b32 v8, v19, v20 offset1:66
	ds_write2_b32 v8, v21, v22 offset0:132 offset1:198
	ds_write2_b32 v7, v23, v24 offset0:8 offset1:74
	ds_write2_b32 v7, v25, v26 offset0:140 offset1:206
	v_add_u32_e32 v7, 0x800, v8
	ds_write2_b32 v7, v27, v28 offset0:16 offset1:82
	ds_write2_b32 v7, v29, v30 offset0:148 offset1:214
	v_add_u32_e32 v7, 0xc00, v8
	ds_write2_b32 v7, v31, v32 offset0:24 offset1:90
	ds_write2_b32 v7, v33, v34 offset0:156 offset1:222
	v_add_u32_e32 v7, 0x1000, v8
	ds_write2_b32 v7, v35, v36 offset0:32 offset1:98
	ds_write2_b32 v7, v37, v38 offset0:164 offset1:230
	v_add_u32_e32 v7, 0x1400, v8
	ds_write2_b32 v7, v39, v40 offset0:40 offset1:106
	ds_write2_b32 v7, v41, v42 offset0:172 offset1:238
	v_add_u32_e32 v7, 0x1800, v8
	ds_write2_b32 v7, v43, v44 offset0:48 offset1:114
	ds_write2_b32 v7, v45, v46 offset0:180 offset1:246
	v_add_u32_e32 v7, 0x1c00, v8
	ds_write2_b32 v7, v47, v48 offset0:56 offset1:122
	ds_write2_b32 v7, v16, v6 offset0:188 offset1:254
	s_waitcnt lgkmcnt(0)
	ds_read_b32 v6, v10
	ds_read_b32 v7, v10 offset:132
	v_lshl_add_u64 v[4:5], s[24:25], 0, v[4:5]
	v_lshl_add_u64 v[4:5], v[4:5], 0, v[144:145]
	v_lshlrev_b32_e32 v144, 1, v2
	s_waitcnt lgkmcnt(1)
	v_add_u32_e32 v6, 0x8000, v6
	s_waitcnt lgkmcnt(0)
	v_add_u32_e32 v7, 0x8000, v7
	v_perm_b32 v16, v7, v6, s81
	ds_read_b32 v6, v10 offset:264
	ds_read_b32 v7, v10 offset:396
	v_lshl_add_u64 v[4:5], v[4:5], 0, v[144:145]
	s_waitcnt lgkmcnt(1)
	v_add_u32_e32 v6, 0x8000, v6
	s_waitcnt lgkmcnt(0)
	v_add_u32_e32 v7, 0x8000, v7
	v_perm_b32 v17, v7, v6, s81
	ds_read_b32 v6, v10 offset:528
	ds_read_b32 v7, v10 offset:660
	s_waitcnt lgkmcnt(1)
	v_add_u32_e32 v6, 0x8000, v6
	s_waitcnt lgkmcnt(0)
	v_add_u32_e32 v7, 0x8000, v7
	v_perm_b32 v18, v7, v6, s81
	ds_read_b32 v6, v10 offset:792
	ds_read_b32 v7, v10 offset:924
	s_waitcnt lgkmcnt(1)
	v_add_u32_e32 v6, 0x8000, v6
	s_waitcnt lgkmcnt(0)
	v_add_u32_e32 v7, 0x8000, v7
	v_perm_b32 v19, v7, v6, s81
	v_or_b32_e32 v6, v15, v9
	v_lshlrev_b32_e32 v144, 12, v6
	v_lshl_add_u64 v[6:7], v[4:5], 0, v[144:145]
	flat_store_dwordx4 v[6:7], v[16:19]
	ds_read_b32 v6, v10 offset:32
	ds_read_b32 v7, v10 offset:164
	s_waitcnt lgkmcnt(0)
	v_add_u32_e32 v6, 0x8000, v6
	v_add_u32_e32 v7, 0x8000, v7
	v_perm_b32 v16, v7, v6, s81
	ds_read_b32 v6, v10 offset:296
	ds_read_b32 v7, v10 offset:428
	s_waitcnt lgkmcnt(0)
	v_add_u32_e32 v6, 0x8000, v6
	v_add_u32_e32 v7, 0x8000, v7
	v_perm_b32 v17, v7, v6, s81
	ds_read_b32 v6, v10 offset:560
	ds_read_b32 v7, v10 offset:692
	s_waitcnt lgkmcnt(0)
	v_add_u32_e32 v6, 0x8000, v6
	v_add_u32_e32 v7, 0x8000, v7
	v_perm_b32 v18, v7, v6, s81
	ds_read_b32 v6, v10 offset:824
	ds_read_b32 v7, v10 offset:956
	s_waitcnt lgkmcnt(0)
	v_add_u32_e32 v6, 0x8000, v6
	v_add_u32_e32 v7, 0x8000, v7
	v_perm_b32 v19, v7, v6, s81
	v_or_b32_e32 v6, v15, v11
	v_lshlrev_b32_e32 v144, 12, v6
	v_lshl_add_u64 v[6:7], v[4:5], 0, v[144:145]
	flat_store_dwordx4 v[6:7], v[16:19]
	ds_read_b32 v6, v10 offset:64
	ds_read_b32 v7, v10 offset:196
	s_waitcnt lgkmcnt(0)
	v_add_u32_e32 v6, 0x8000, v6
	v_add_u32_e32 v7, 0x8000, v7
	v_perm_b32 v16, v7, v6, s81
	ds_read_b32 v6, v10 offset:328
	ds_read_b32 v7, v10 offset:460
	s_waitcnt lgkmcnt(0)
	v_add_u32_e32 v6, 0x8000, v6
	v_add_u32_e32 v7, 0x8000, v7
	v_perm_b32 v17, v7, v6, s81
	ds_read_b32 v6, v10 offset:592
	ds_read_b32 v7, v10 offset:724
	s_waitcnt lgkmcnt(0)
	v_add_u32_e32 v6, 0x8000, v6
	v_add_u32_e32 v7, 0x8000, v7
	v_perm_b32 v18, v7, v6, s81
	ds_read_b32 v6, v10 offset:856
	ds_read_b32 v7, v10 offset:988
	s_waitcnt lgkmcnt(0)
	v_add_u32_e32 v6, 0x8000, v6
	v_add_u32_e32 v7, 0x8000, v7
	v_perm_b32 v19, v7, v6, s81
	v_or_b32_e32 v6, v15, v13
	v_lshlrev_b32_e32 v144, 12, v6
	v_lshl_add_u64 v[6:7], v[4:5], 0, v[144:145]
	flat_store_dwordx4 v[6:7], v[16:19]
	ds_read_b32 v6, v10 offset:96
	ds_read_b32 v7, v10 offset:228
	s_waitcnt lgkmcnt(0)
	v_add_u32_e32 v6, 0x8000, v6
	v_add_u32_e32 v7, 0x8000, v7
	v_perm_b32 v16, v7, v6, s81
	ds_read_b32 v6, v10 offset:360
	ds_read_b32 v7, v10 offset:492
	s_waitcnt lgkmcnt(0)
	v_add_u32_e32 v6, 0x8000, v6
	v_add_u32_e32 v7, 0x8000, v7
	v_perm_b32 v17, v7, v6, s81
	ds_read_b32 v6, v10 offset:624
	ds_read_b32 v7, v10 offset:756
	s_waitcnt lgkmcnt(0)
	v_add_u32_e32 v6, 0x8000, v6
	v_add_u32_e32 v7, 0x8000, v7
	v_perm_b32 v18, v7, v6, s81
	ds_read_b32 v6, v10 offset:888
	ds_read_b32 v7, v10 offset:1020
	s_waitcnt lgkmcnt(0)
	v_add_u32_e32 v6, 0x8000, v6
	v_add_u32_e32 v7, 0x8000, v7
	v_perm_b32 v19, v7, v6, s81
	v_or_b32_e32 v6, v15, v12
	v_lshlrev_b32_e32 v144, 12, v6
	v_lshl_add_u64 v[4:5], v[4:5], 0, v[144:145]
	flat_store_dwordx4 v[4:5], v[16:19]
	s_waitcnt lgkmcnt(0)
